# speedup vs baseline: 1.0027x; 1.0027x over previous
; __device__ __forceinline__ void gmlp_fast(KArgs ap, int l, LAS unsigned char* lds, const Ctx cx) {
;     ...
;             for (int e = 0; e < 4; ++e) { const int chl = lane + 64 * e, ch = 256 * k + chl;
;                 const float gg = lng[ch], bb = lnb[ch];
;                 float vv[16];
; #pragma unroll
;                 for (int i = 0; i < 16; ++i) { const int s = wave * 16 + i; const float x = gelu_tanh(bf2f(z[(t0 + s) * DIN + ZGV + ch])); vv[i] = (x - ST[2 * s]) * ST[2 * s + 1] * gg + bb; }
.LBB0_162:
	v_lshl_add_u64 v[34:35], v[6:7], 0, s[20:21]
	global_load_dword v8, v[2:3], off offset:-256
	global_load_dword v10, v[4:5], off offset:-256
	global_load_dword v232, v[2:3], off
	global_load_dword v233, v[4:5], off
	s_add_u32 s88, s18, s20
	s_addc_u32 s89, s19, s21
	s_add_u32 s82, s88, 0x13001000
	s_addc_u32 s83, s89, 0
	global_load_ushort v200, v234, s[82:83] offset:512
	s_add_u32 s84, s88, 0x13003000
	s_addc_u32 s85, s89, 0
	global_load_ushort v201, v234, s[84:85] offset:3584
	s_add_u32 s86, s88, 0x13002000
	s_addc_u32 s87, s89, 0
	global_load_ushort v202, v234, s[86:87] offset:2048
	s_add_u32 s82, s88, 0x13005000
	s_addc_u32 s83, s89, 0
	global_load_ushort v203, v234, s[82:83] offset:1024
	s_add_u32 s84, s88, 0x13006000
	s_addc_u32 s85, s89, 0
	global_load_ushort v204, v234, s[84:85] offset:2560
	s_add_u32 s86, s88, 0x13009000
	s_addc_u32 s87, s89, 0
	global_load_ushort v205, v234, s[86:87] offset:1536
	s_add_u32 s82, s88, 0x13008000
	s_addc_u32 s83, s89, 0
	global_load_ushort v206, v234, s[82:83]
	s_add_u32 s84, s88, 0x1300a000
	s_addc_u32 s85, s89, 0
	global_load_ushort v207, v234, s[84:85] offset:3072
	s_add_u32 s86, s88, 0x1300c000
	s_addc_u32 s87, s89, 0
	global_load_ushort v208, v234, s[86:87] offset:512
	s_add_u32 s82, s88, 0x1300e000
	s_addc_u32 s83, s89, 0
	global_load_ushort v209, v234, s[82:83] offset:3584
	s_add_u32 s84, s88, 0x1300d000
	s_addc_u32 s85, s89, 0
	global_load_ushort v210, v234, s[84:85] offset:2048
	s_add_u32 s86, s88, 0x13010000
	s_addc_u32 s87, s89, 0
	global_load_ushort v211, v234, s[86:87] offset:1024
	s_add_u32 s82, s88, 0x13011000
	s_addc_u32 s83, s89, 0
	global_load_ushort v212, v234, s[82:83] offset:2560
	s_add_u32 s84, s88, 0x13014000
	s_addc_u32 s85, s89, 0
	global_load_ushort v213, v234, s[84:85] offset:1536
	s_add_u32 s86, s88, 0x13015000
	s_addc_u32 s87, s89, 0
	global_load_ushort v214, v234, s[86:87] offset:3072
	s_add_u32 s82, s88, 0x13013000
	s_addc_u32 s83, s89, 0
	global_load_ushort v215, v234, s[82:83]
	s_add_u32 s84, s88, 0x13001000
	s_addc_u32 s85, s89, 0
	global_load_ushort v216, v235, s[84:85] offset:512
	s_add_u32 s86, s88, 0x13003000
	s_addc_u32 s87, s89, 0
	global_load_ushort v217, v235, s[86:87] offset:3584
	s_add_u32 s82, s88, 0x13002000
	s_addc_u32 s83, s89, 0
	global_load_ushort v218, v235, s[82:83] offset:2048
	s_add_u32 s84, s88, 0x13005000
	s_addc_u32 s85, s89, 0
	global_load_ushort v219, v235, s[84:85] offset:1024
	s_add_u32 s86, s88, 0x13006000
	s_addc_u32 s87, s89, 0
	global_load_ushort v220, v235, s[86:87] offset:2560
	s_add_u32 s82, s88, 0x13009000
	s_addc_u32 s83, s89, 0
	global_load_ushort v221, v235, s[82:83] offset:1536
	s_add_u32 s84, s88, 0x13008000
	s_addc_u32 s85, s89, 0
	global_load_ushort v222, v235, s[84:85]
	s_add_u32 s86, s88, 0x1300a000
	s_addc_u32 s87, s89, 0
	global_load_ushort v223, v235, s[86:87] offset:3072
	s_add_u32 s82, s88, 0x1300c000
	s_addc_u32 s83, s89, 0
	global_load_ushort v224, v235, s[82:83] offset:512
	s_add_u32 s84, s88, 0x1300e000
	s_addc_u32 s85, s89, 0
	global_load_ushort v225, v235, s[84:85] offset:3584
	s_add_u32 s86, s88, 0x1300d000
	s_addc_u32 s87, s89, 0
	global_load_ushort v226, v235, s[86:87] offset:2048
	s_add_u32 s82, s88, 0x13010000
	s_addc_u32 s83, s89, 0
	global_load_ushort v227, v235, s[82:83] offset:1024
	s_add_u32 s84, s88, 0x13011000
	s_addc_u32 s85, s89, 0
	global_load_ushort v228, v235, s[84:85] offset:2560
	s_add_u32 s86, s88, 0x13014000
	s_addc_u32 s87, s89, 0
	global_load_ushort v229, v235, s[86:87] offset:1536
	s_add_u32 s82, s88, 0x13013000
	s_addc_u32 s83, s89, 0
	global_load_ushort v230, v235, s[82:83]
	s_add_u32 s84, s88, 0x13015000
	s_addc_u32 s85, s89, 0
	global_load_ushort v231, v235, s[84:85] offset:3072
	s_add_i32 s22, 0, 0x11000
	s_add_i32 s23, s22, s30
	v_mov_b32_e32 v11, s23
	ds_read_b128 v[140:143], v11
	ds_read_b128 v[144:147], v11 offset:16
	s_add_i32 s23, s22, s31
	v_mov_b32_e32 v12, s23
	ds_read_b128 v[148:151], v12
	ds_read_b128 v[174:177], v12 offset:16
	s_add_i32 s23, s22, s38
	v_mov_b32_e32 v13, s23
	ds_read_b128 v[178:181], v13
	ds_read_b128 v[182:185], v13 offset:16
	s_add_i32 s23, s22, s39
	v_mov_b32_e32 v14, s23
	ds_read_b128 v[186:189], v14
	ds_read_b128 v[16:19], v14 offset:16
	s_waitcnt vmcnt(24)
	s_waitcnt lgkmcnt(0)
; #define LAS __attribute__((address_space(3)))
; __device__ __forceinline__ unsigned pk2(float lo, float hi) { return f2bf(lo) | (f2bf(hi) << 16); }
; __device__ __forceinline__ void gmlp_fast(KArgs ap, int l, LAS unsigned char* lds, const Ctx cx) {
;     ...
;                 for (int i = 0; i < 16; ++i) { const int s = wave * 16 + i; const float x = gelu_tanh(bf2f(z[(t0 + s) * DIN + ZGV + ch])); vv[i] = (x - ST[2 * s]) * ST[2 * s + 1] * gg + bb; }
;                 u32x4 w0, w1;
;                 w0.x = pk2(vv[0], vv[1]); w0.y = pk2(vv[2], vv[3]); w0.z = pk2(vv[4], vv[5]); w0.w = pk2(vv[6], vv[7]);
;                 w1.x = pk2(vv[8], vv[9]); w1.y = pk2(vv[10], vv[11]); w1.z = pk2(vv[12], vv[13]); w1.w = pk2(vv[14], vv[15]);
;                 *(LAS u32x4*)(VT + chl * 272 + wave * 32) = w0; *(LAS u32x4*)(VT + chl * 272 + wave * 32 + 16) = w1; }
	v_lshlrev_b32_e32 v113, 16, v200
	v_lshlrev_b32_e32 v114, 16, v202
	v_lshlrev_b32_e32 v115, 16, v201
	v_lshlrev_b32_e32 v116, 16, v203
	v_lshlrev_b32_e32 v117, 16, v204
	v_lshlrev_b32_e32 v118, 16, v206
	v_lshlrev_b32_e32 v119, 16, v205
	v_lshlrev_b32_e32 v120, 16, v207
	v_mul_f32_e32 v121, 0x3d372713, v113
	v_mul_f32_e32 v122, 0x3d372713, v114
	v_mul_f32_e32 v123, 0x3d372713, v115
	v_mul_f32_e32 v124, 0x3d372713, v116
	v_mul_f32_e32 v125, 0x3d372713, v117
	v_mul_f32_e32 v126, 0x3d372713, v118
	v_mul_f32_e32 v127, 0x3d372713, v119
	v_mul_f32_e32 v128, 0x3d372713, v120
	v_mul_f32_e32 v121, v121, v113
	v_mul_f32_e32 v122, v122, v114
	v_mul_f32_e32 v123, v123, v115
	v_mul_f32_e32 v124, v124, v116
	v_mul_f32_e32 v125, v125, v117
	v_mul_f32_e32 v126, v126, v118
	v_mul_f32_e32 v127, v127, v119
	v_mul_f32_e32 v128, v128, v120
	v_fma_f32 v121, v121, v113, v113
	v_fma_f32 v122, v122, v114, v114
	v_fma_f32 v123, v123, v115, v115
	v_fma_f32 v124, v124, v116, v116
	v_fma_f32 v125, v125, v117, v117
	v_fma_f32 v126, v126, v118, v118
	v_fma_f32 v127, v127, v119, v119
	v_fma_f32 v128, v128, v120, v120
	v_mul_f32_e32 v121, 0x3f4c422a, v121
	v_mul_f32_e32 v122, 0x3f4c422a, v122
	v_mul_f32_e32 v123, 0x3f4c422a, v123
	v_mul_f32_e32 v124, 0x3f4c422a, v124
	v_mul_f32_e32 v125, 0x3f4c422a, v125
	v_mul_f32_e32 v126, 0x3f4c422a, v126
	v_mul_f32_e32 v127, 0x3f4c422a, v127
	v_mul_f32_e32 v128, 0x3f4c422a, v128
	v_add_f32_e32 v121, v121, v121
	v_add_f32_e32 v122, v122, v122
	v_add_f32_e32 v123, v123, v123
	v_add_f32_e32 v124, v124, v124
	v_add_f32_e32 v125, v125, v125
	v_add_f32_e32 v126, v126, v126
	v_add_f32_e32 v127, v127, v127
	v_add_f32_e32 v128, v128, v128
	v_mul_f32_e32 v121, 0x3fb8aa3b, v121
	v_mul_f32_e32 v122, 0x3fb8aa3b, v122
	v_mul_f32_e32 v123, 0x3fb8aa3b, v123
	v_mul_f32_e32 v124, 0x3fb8aa3b, v124
	v_mul_f32_e32 v125, 0x3fb8aa3b, v125
	v_mul_f32_e32 v126, 0x3fb8aa3b, v126
	v_mul_f32_e32 v127, 0x3fb8aa3b, v127
	v_mul_f32_e32 v128, 0x3fb8aa3b, v128
	v_exp_f32_e32 v121, v121
	v_exp_f32_e32 v122, v122
	v_exp_f32_e32 v123, v123
	v_exp_f32_e32 v124, v124
	v_exp_f32_e32 v125, v125
	v_exp_f32_e32 v126, v126
	v_exp_f32_e32 v127, v127
	v_exp_f32_e32 v128, v128
	v_mul_f32_e32 v129, 0.5, v113
	v_mul_f32_e32 v130, 0.5, v114
	v_mul_f32_e32 v131, 0.5, v115
	v_mul_f32_e32 v132, 0.5, v116
	v_mul_f32_e32 v133, 0.5, v117
	v_mul_f32_e32 v134, 0.5, v118
	v_mul_f32_e32 v135, 0.5, v119
	v_mul_f32_e32 v138, 0.5, v120
	v_add_f32_e32 v121, 1.0, v121
	v_add_f32_e32 v122, 1.0, v122
	v_add_f32_e32 v123, 1.0, v123
	v_add_f32_e32 v124, 1.0, v124
	v_add_f32_e32 v125, 1.0, v125
	v_add_f32_e32 v126, 1.0, v126
	v_add_f32_e32 v127, 1.0, v127
	v_add_f32_e32 v128, 1.0, v128
	v_rcp_f32_e32 v121, v121
	v_rcp_f32_e32 v122, v122
	v_rcp_f32_e32 v123, v123
	v_rcp_f32_e32 v124, v124
	v_rcp_f32_e32 v125, v125
	v_rcp_f32_e32 v126, v126
	v_rcp_f32_e32 v127, v127
	v_rcp_f32_e32 v128, v128
	v_fma_f32 v121, v121, -2.0, 1.0
	v_fma_f32 v122, v122, -2.0, 1.0
	v_fma_f32 v123, v123, -2.0, 1.0
	v_fma_f32 v124, v124, -2.0, 1.0
	v_fma_f32 v125, v125, -2.0, 1.0
	v_fma_f32 v126, v126, -2.0, 1.0
	v_fma_f32 v127, v127, -2.0, 1.0
	v_fma_f32 v128, v128, -2.0, 1.0
	v_add_f32_e32 v121, 1.0, v121
	v_add_f32_e32 v122, 1.0, v122
	v_add_f32_e32 v123, 1.0, v123
	v_add_f32_e32 v124, 1.0, v124
	v_add_f32_e32 v125, 1.0, v125
	v_add_f32_e32 v126, 1.0, v126
	v_add_f32_e32 v127, 1.0, v127
	v_add_f32_e32 v128, 1.0, v128
	v_fma_f32 v113, v129, v121, -v140
	v_fma_f32 v114, v130, v122, -v142
	v_fma_f32 v115, v131, v123, -v144
	v_fma_f32 v116, v132, v124, -v146
	v_fma_f32 v117, v133, v125, -v148
	v_fma_f32 v118, v134, v126, -v150
	v_fma_f32 v119, v135, v127, -v174
	v_fma_f32 v120, v138, v128, -v176
	v_mul_f32_e32 v113, v141, v113
	v_mul_f32_e32 v114, v143, v114
	v_mul_f32_e32 v115, v145, v115
	v_mul_f32_e32 v116, v147, v116
	v_mul_f32_e32 v117, v149, v117
	v_mul_f32_e32 v118, v151, v118
	v_mul_f32_e32 v119, v175, v119
	v_mul_f32_e32 v120, v177, v120
	v_fma_f32 v113, v8, v113, v10
	v_fma_f32 v114, v8, v114, v10
	v_fma_f32 v115, v8, v115, v10
	v_fma_f32 v116, v8, v116, v10
	v_fma_f32 v117, v8, v117, v10
	v_fma_f32 v118, v8, v118, v10
	v_fma_f32 v119, v8, v119, v10
	v_fma_f32 v120, v8, v120, v10
	v_cvt_pk_bf16_f32 v236, v113, v114
	v_cvt_pk_bf16_f32 v237, v115, v116
	v_cvt_pk_bf16_f32 v238, v117, v118
	v_cvt_pk_bf16_f32 v239, v119, v120
	ds_write_b128 v9, v[236:239]
	s_waitcnt vmcnt(16)
; #define LAS __attribute__((address_space(3)))
; __device__ __forceinline__ unsigned pk2(float lo, float hi) { return f2bf(lo) | (f2bf(hi) << 16); }
; __device__ __forceinline__ void gmlp_fast(KArgs ap, int l, LAS unsigned char* lds, const Ctx cx) {
;     ...
;                 for (int i = 0; i < 16; ++i) { const int s = wave * 16 + i; const float x = gelu_tanh(bf2f(z[(t0 + s) * DIN + ZGV + ch])); vv[i] = (x - ST[2 * s]) * ST[2 * s + 1] * gg + bb; }
;                 u32x4 w0, w1;
;                 w0.x = pk2(vv[0], vv[1]); w0.y = pk2(vv[2], vv[3]); w0.z = pk2(vv[4], vv[5]); w0.w = pk2(vv[6], vv[7]);
;                 w1.x = pk2(vv[8], vv[9]); w1.y = pk2(vv[10], vv[11]); w1.z = pk2(vv[12], vv[13]); w1.w = pk2(vv[14], vv[15]);
;                 *(LAS u32x4*)(VT + chl * 272 + wave * 32) = w0; *(LAS u32x4*)(VT + chl * 272 + wave * 32 + 16) = w1; }
	v_lshlrev_b32_e32 v113, 16, v208
	v_lshlrev_b32_e32 v114, 16, v210
	v_lshlrev_b32_e32 v115, 16, v209
	v_lshlrev_b32_e32 v116, 16, v211
	v_lshlrev_b32_e32 v117, 16, v212
	v_lshlrev_b32_e32 v118, 16, v215
	v_lshlrev_b32_e32 v119, 16, v213
	v_lshlrev_b32_e32 v120, 16, v214
	v_mul_f32_e32 v121, 0x3d372713, v113
	v_mul_f32_e32 v122, 0x3d372713, v114
	v_mul_f32_e32 v123, 0x3d372713, v115
	v_mul_f32_e32 v124, 0x3d372713, v116
	v_mul_f32_e32 v125, 0x3d372713, v117
	v_mul_f32_e32 v126, 0x3d372713, v118
	v_mul_f32_e32 v127, 0x3d372713, v119
	v_mul_f32_e32 v128, 0x3d372713, v120
	v_mul_f32_e32 v121, v121, v113
	v_mul_f32_e32 v122, v122, v114
	v_mul_f32_e32 v123, v123, v115
	v_mul_f32_e32 v124, v124, v116
	v_mul_f32_e32 v125, v125, v117
	v_mul_f32_e32 v126, v126, v118
	v_mul_f32_e32 v127, v127, v119
	v_mul_f32_e32 v128, v128, v120
	v_fma_f32 v121, v121, v113, v113
	v_fma_f32 v122, v122, v114, v114
	v_fma_f32 v123, v123, v115, v115
	v_fma_f32 v124, v124, v116, v116
	v_fma_f32 v125, v125, v117, v117
	v_fma_f32 v126, v126, v118, v118
	v_fma_f32 v127, v127, v119, v119
	v_fma_f32 v128, v128, v120, v120
	v_mul_f32_e32 v121, 0x3f4c422a, v121
	v_mul_f32_e32 v122, 0x3f4c422a, v122
	v_mul_f32_e32 v123, 0x3f4c422a, v123
	v_mul_f32_e32 v124, 0x3f4c422a, v124
	v_mul_f32_e32 v125, 0x3f4c422a, v125
	v_mul_f32_e32 v126, 0x3f4c422a, v126
	v_mul_f32_e32 v127, 0x3f4c422a, v127
	v_mul_f32_e32 v128, 0x3f4c422a, v128
	v_add_f32_e32 v121, v121, v121
	v_add_f32_e32 v122, v122, v122
	v_add_f32_e32 v123, v123, v123
	v_add_f32_e32 v124, v124, v124
	v_add_f32_e32 v125, v125, v125
	v_add_f32_e32 v126, v126, v126
	v_add_f32_e32 v127, v127, v127
	v_add_f32_e32 v128, v128, v128
	v_mul_f32_e32 v121, 0x3fb8aa3b, v121
	v_mul_f32_e32 v122, 0x3fb8aa3b, v122
	v_mul_f32_e32 v123, 0x3fb8aa3b, v123
	v_mul_f32_e32 v124, 0x3fb8aa3b, v124
	v_mul_f32_e32 v125, 0x3fb8aa3b, v125
	v_mul_f32_e32 v126, 0x3fb8aa3b, v126
	v_mul_f32_e32 v127, 0x3fb8aa3b, v127
	v_mul_f32_e32 v128, 0x3fb8aa3b, v128
	v_exp_f32_e32 v121, v121
	v_exp_f32_e32 v122, v122
	v_exp_f32_e32 v123, v123
	v_exp_f32_e32 v124, v124
	v_exp_f32_e32 v125, v125
	v_exp_f32_e32 v126, v126
	v_exp_f32_e32 v127, v127
	v_exp_f32_e32 v128, v128
	v_mul_f32_e32 v129, 0.5, v113
	v_mul_f32_e32 v130, 0.5, v114
	v_mul_f32_e32 v131, 0.5, v115
	v_mul_f32_e32 v132, 0.5, v116
	v_mul_f32_e32 v133, 0.5, v117
	v_mul_f32_e32 v134, 0.5, v118
	v_mul_f32_e32 v135, 0.5, v119
	v_mul_f32_e32 v138, 0.5, v120
	v_add_f32_e32 v121, 1.0, v121
	v_add_f32_e32 v122, 1.0, v122
	v_add_f32_e32 v123, 1.0, v123
	v_add_f32_e32 v124, 1.0, v124
	v_add_f32_e32 v125, 1.0, v125
	v_add_f32_e32 v126, 1.0, v126
	v_add_f32_e32 v127, 1.0, v127
	v_add_f32_e32 v128, 1.0, v128
	v_rcp_f32_e32 v121, v121
	v_rcp_f32_e32 v122, v122
	v_rcp_f32_e32 v123, v123
	v_rcp_f32_e32 v124, v124
	v_rcp_f32_e32 v125, v125
	v_rcp_f32_e32 v126, v126
	v_rcp_f32_e32 v127, v127
	v_rcp_f32_e32 v128, v128
	v_fma_f32 v121, v121, -2.0, 1.0
	v_fma_f32 v122, v122, -2.0, 1.0
	v_fma_f32 v123, v123, -2.0, 1.0
	v_fma_f32 v124, v124, -2.0, 1.0
	v_fma_f32 v125, v125, -2.0, 1.0
	v_fma_f32 v126, v126, -2.0, 1.0
	v_fma_f32 v127, v127, -2.0, 1.0
	v_fma_f32 v128, v128, -2.0, 1.0
	v_add_f32_e32 v121, 1.0, v121
	v_add_f32_e32 v122, 1.0, v122
	v_add_f32_e32 v123, 1.0, v123
	v_add_f32_e32 v124, 1.0, v124
	v_add_f32_e32 v125, 1.0, v125
	v_add_f32_e32 v126, 1.0, v126
	v_add_f32_e32 v127, 1.0, v127
	v_add_f32_e32 v128, 1.0, v128
	v_fma_f32 v113, v129, v121, -v178
	v_fma_f32 v114, v130, v122, -v180
	v_fma_f32 v115, v131, v123, -v182
	v_fma_f32 v116, v132, v124, -v184
	v_fma_f32 v117, v133, v125, -v186
	v_fma_f32 v118, v134, v126, -v188
	v_fma_f32 v119, v135, v127, -v16
	v_fma_f32 v120, v138, v128, -v18
	v_mul_f32_e32 v113, v179, v113
	v_mul_f32_e32 v114, v181, v114
	v_mul_f32_e32 v115, v183, v115
	v_mul_f32_e32 v116, v185, v116
	v_mul_f32_e32 v117, v187, v117
	v_mul_f32_e32 v118, v189, v118
	v_mul_f32_e32 v119, v17, v119
	v_mul_f32_e32 v120, v19, v120
	v_fma_f32 v113, v8, v113, v10
	v_fma_f32 v114, v8, v114, v10
	v_fma_f32 v115, v8, v115, v10
	v_fma_f32 v116, v8, v116, v10
	v_fma_f32 v117, v8, v117, v10
	v_fma_f32 v118, v8, v118, v10
	v_fma_f32 v119, v8, v119, v10
	v_fma_f32 v120, v8, v120, v10
	v_cvt_pk_bf16_f32 v236, v113, v114
	v_cvt_pk_bf16_f32 v237, v115, v116
	v_cvt_pk_bf16_f32 v238, v117, v118
	v_cvt_pk_bf16_f32 v239, v119, v120
	ds_write_b128 v9, v[236:239] offset:16
	s_waitcnt vmcnt(8)
; #define LAS __attribute__((address_space(3)))
; __device__ __forceinline__ unsigned pk2(float lo, float hi) { return f2bf(lo) | (f2bf(hi) << 16); }
; __device__ __forceinline__ void gmlp_fast(KArgs ap, int l, LAS unsigned char* lds, const Ctx cx) {
;     ...
;                 for (int i = 0; i < 16; ++i) { const int s = wave * 16 + i; const float x = gelu_tanh(bf2f(z[(t0 + s) * DIN + ZGV + ch])); vv[i] = (x - ST[2 * s]) * ST[2 * s + 1] * gg + bb; }
;                 u32x4 w0, w1;
;                 w0.x = pk2(vv[0], vv[1]); w0.y = pk2(vv[2], vv[3]); w0.z = pk2(vv[4], vv[5]); w0.w = pk2(vv[6], vv[7]);
;                 w1.x = pk2(vv[8], vv[9]); w1.y = pk2(vv[10], vv[11]); w1.z = pk2(vv[12], vv[13]); w1.w = pk2(vv[14], vv[15]);
;                 *(LAS u32x4*)(VT + chl * 272 + wave * 32) = w0; *(LAS u32x4*)(VT + chl * 272 + wave * 32 + 16) = w1; }
	v_lshlrev_b32_e32 v113, 16, v216
	v_lshlrev_b32_e32 v114, 16, v218
	v_lshlrev_b32_e32 v115, 16, v217
	v_lshlrev_b32_e32 v116, 16, v219
	v_lshlrev_b32_e32 v117, 16, v220
	v_lshlrev_b32_e32 v118, 16, v222
	v_lshlrev_b32_e32 v119, 16, v221
	v_lshlrev_b32_e32 v120, 16, v223
	v_mul_f32_e32 v121, 0x3d372713, v113
	v_mul_f32_e32 v122, 0x3d372713, v114
	v_mul_f32_e32 v123, 0x3d372713, v115
	v_mul_f32_e32 v124, 0x3d372713, v116
	v_mul_f32_e32 v125, 0x3d372713, v117
	v_mul_f32_e32 v126, 0x3d372713, v118
	v_mul_f32_e32 v127, 0x3d372713, v119
	v_mul_f32_e32 v128, 0x3d372713, v120
	v_mul_f32_e32 v121, v121, v113
	v_mul_f32_e32 v122, v122, v114
	v_mul_f32_e32 v123, v123, v115
	v_mul_f32_e32 v124, v124, v116
	v_mul_f32_e32 v125, v125, v117
	v_mul_f32_e32 v126, v126, v118
	v_mul_f32_e32 v127, v127, v119
	v_mul_f32_e32 v128, v128, v120
	v_fma_f32 v121, v121, v113, v113
	v_fma_f32 v122, v122, v114, v114
	v_fma_f32 v123, v123, v115, v115
	v_fma_f32 v124, v124, v116, v116
	v_fma_f32 v125, v125, v117, v117
	v_fma_f32 v126, v126, v118, v118
	v_fma_f32 v127, v127, v119, v119
	v_fma_f32 v128, v128, v120, v120
	v_mul_f32_e32 v121, 0x3f4c422a, v121
	v_mul_f32_e32 v122, 0x3f4c422a, v122
	v_mul_f32_e32 v123, 0x3f4c422a, v123
	v_mul_f32_e32 v124, 0x3f4c422a, v124
	v_mul_f32_e32 v125, 0x3f4c422a, v125
	v_mul_f32_e32 v126, 0x3f4c422a, v126
	v_mul_f32_e32 v127, 0x3f4c422a, v127
	v_mul_f32_e32 v128, 0x3f4c422a, v128
	v_add_f32_e32 v121, v121, v121
	v_add_f32_e32 v122, v122, v122
	v_add_f32_e32 v123, v123, v123
	v_add_f32_e32 v124, v124, v124
	v_add_f32_e32 v125, v125, v125
	v_add_f32_e32 v126, v126, v126
	v_add_f32_e32 v127, v127, v127
	v_add_f32_e32 v128, v128, v128
	v_mul_f32_e32 v121, 0x3fb8aa3b, v121
	v_mul_f32_e32 v122, 0x3fb8aa3b, v122
	v_mul_f32_e32 v123, 0x3fb8aa3b, v123
	v_mul_f32_e32 v124, 0x3fb8aa3b, v124
	v_mul_f32_e32 v125, 0x3fb8aa3b, v125
	v_mul_f32_e32 v126, 0x3fb8aa3b, v126
	v_mul_f32_e32 v127, 0x3fb8aa3b, v127
	v_mul_f32_e32 v128, 0x3fb8aa3b, v128
	v_exp_f32_e32 v121, v121
	v_exp_f32_e32 v122, v122
	v_exp_f32_e32 v123, v123
	v_exp_f32_e32 v124, v124
	v_exp_f32_e32 v125, v125
	v_exp_f32_e32 v126, v126
	v_exp_f32_e32 v127, v127
	v_exp_f32_e32 v128, v128
	v_mul_f32_e32 v129, 0.5, v113
	v_mul_f32_e32 v130, 0.5, v114
	v_mul_f32_e32 v131, 0.5, v115
	v_mul_f32_e32 v132, 0.5, v116
	v_mul_f32_e32 v133, 0.5, v117
	v_mul_f32_e32 v134, 0.5, v118
	v_mul_f32_e32 v135, 0.5, v119
	v_mul_f32_e32 v138, 0.5, v120
	v_add_f32_e32 v121, 1.0, v121
	v_add_f32_e32 v122, 1.0, v122
	v_add_f32_e32 v123, 1.0, v123
	v_add_f32_e32 v124, 1.0, v124
	v_add_f32_e32 v125, 1.0, v125
	v_add_f32_e32 v126, 1.0, v126
	v_add_f32_e32 v127, 1.0, v127
	v_add_f32_e32 v128, 1.0, v128
	v_rcp_f32_e32 v121, v121
	v_rcp_f32_e32 v122, v122
	v_rcp_f32_e32 v123, v123
	v_rcp_f32_e32 v124, v124
	v_rcp_f32_e32 v125, v125
	v_rcp_f32_e32 v126, v126
	v_rcp_f32_e32 v127, v127
	v_rcp_f32_e32 v128, v128
	v_fma_f32 v121, v121, -2.0, 1.0
	v_fma_f32 v122, v122, -2.0, 1.0
	v_fma_f32 v123, v123, -2.0, 1.0
	v_fma_f32 v124, v124, -2.0, 1.0
	v_fma_f32 v125, v125, -2.0, 1.0
	v_fma_f32 v126, v126, -2.0, 1.0
	v_fma_f32 v127, v127, -2.0, 1.0
	v_fma_f32 v128, v128, -2.0, 1.0
	v_add_f32_e32 v121, 1.0, v121
	v_add_f32_e32 v122, 1.0, v122
	v_add_f32_e32 v123, 1.0, v123
	v_add_f32_e32 v124, 1.0, v124
	v_add_f32_e32 v125, 1.0, v125
	v_add_f32_e32 v126, 1.0, v126
	v_add_f32_e32 v127, 1.0, v127
	v_add_f32_e32 v128, 1.0, v128
	v_fma_f32 v113, v129, v121, -v140
	v_fma_f32 v114, v130, v122, -v142
	v_fma_f32 v115, v131, v123, -v144
	v_fma_f32 v116, v132, v124, -v146
	v_fma_f32 v117, v133, v125, -v148
	v_fma_f32 v118, v134, v126, -v150
	v_fma_f32 v119, v135, v127, -v174
	v_fma_f32 v120, v138, v128, -v176
	v_mul_f32_e32 v113, v141, v113
	v_mul_f32_e32 v114, v143, v114
	v_mul_f32_e32 v115, v145, v115
	v_mul_f32_e32 v116, v147, v116
	v_mul_f32_e32 v117, v149, v117
	v_mul_f32_e32 v118, v151, v118
	v_mul_f32_e32 v119, v175, v119
	v_mul_f32_e32 v120, v177, v120
	v_fma_f32 v113, v232, v113, v233
	v_fma_f32 v114, v232, v114, v233
	v_fma_f32 v115, v232, v115, v233
	v_fma_f32 v116, v232, v116, v233
	v_fma_f32 v117, v232, v117, v233
	v_fma_f32 v118, v232, v118, v233
	v_fma_f32 v119, v232, v119, v233
	v_fma_f32 v120, v232, v120, v233
	v_cvt_pk_bf16_f32 v236, v113, v114
	v_cvt_pk_bf16_f32 v237, v115, v116
	v_cvt_pk_bf16_f32 v238, v117, v118
	v_cvt_pk_bf16_f32 v239, v119, v120
	ds_write_b128 v9, v[236:239] offset:17408
	s_waitcnt vmcnt(0)
; #define LAS __attribute__((address_space(3)))
; __device__ __forceinline__ unsigned pk2(float lo, float hi) { return f2bf(lo) | (f2bf(hi) << 16); }
; __device__ __forceinline__ void gmlp_fast(KArgs ap, int l, LAS unsigned char* lds, const Ctx cx) {
;     ...
;                 for (int i = 0; i < 16; ++i) { const int s = wave * 16 + i; const float x = gelu_tanh(bf2f(z[(t0 + s) * DIN + ZGV + ch])); vv[i] = (x - ST[2 * s]) * ST[2 * s + 1] * gg + bb; }
;                 u32x4 w0, w1;
;                 w0.x = pk2(vv[0], vv[1]); w0.y = pk2(vv[2], vv[3]); w0.z = pk2(vv[4], vv[5]); w0.w = pk2(vv[6], vv[7]);
;                 w1.x = pk2(vv[8], vv[9]); w1.y = pk2(vv[10], vv[11]); w1.z = pk2(vv[12], vv[13]); w1.w = pk2(vv[14], vv[15]);
;                 *(LAS u32x4*)(VT + chl * 272 + wave * 32) = w0; *(LAS u32x4*)(VT + chl * 272 + wave * 32 + 16) = w1; }
;             __syncthreads();
;             const int gl = wave >> 2, tb = wave & 3, g = 2 * k + gl;
;             f32x16 acc[4];
; #pragma unroll
;             for (int ht = 0; ht < 4; ++ht)
; #pragma unroll
;                 for (int i = 0; i < 16; ++i) acc[ht][i] = 0.f;
;             const int tl = 32 * tb + r;
;             const float* wrow = wsp + ((size_t)g * 128 + tl) * 128 + 8 * hh;
;             f32x4 wn0 = *(const f32x4*)wrow, wn1 = *(const f32x4*)(wrow + 4);
	v_lshlrev_b32_e32 v113, 16, v224
	v_lshlrev_b32_e32 v114, 16, v226
	v_lshlrev_b32_e32 v115, 16, v225
	v_lshlrev_b32_e32 v116, 16, v227
	v_lshlrev_b32_e32 v117, 16, v228
	v_lshlrev_b32_e32 v118, 16, v230
	v_lshlrev_b32_e32 v119, 16, v229
	v_lshlrev_b32_e32 v120, 16, v231
	v_mul_f32_e32 v121, 0x3d372713, v113
	v_mul_f32_e32 v122, 0x3d372713, v114
	v_mul_f32_e32 v123, 0x3d372713, v115
	v_mul_f32_e32 v124, 0x3d372713, v116
	v_mul_f32_e32 v125, 0x3d372713, v117
	v_mul_f32_e32 v126, 0x3d372713, v118
	v_mul_f32_e32 v127, 0x3d372713, v119
	v_mul_f32_e32 v128, 0x3d372713, v120
	v_mul_f32_e32 v121, v121, v113
	v_mul_f32_e32 v122, v122, v114
	v_mul_f32_e32 v123, v123, v115
	v_mul_f32_e32 v124, v124, v116
	v_mul_f32_e32 v125, v125, v117
	v_mul_f32_e32 v126, v126, v118
	v_mul_f32_e32 v127, v127, v119
	v_mul_f32_e32 v128, v128, v120
	v_fma_f32 v121, v121, v113, v113
	v_fma_f32 v122, v122, v114, v114
	v_fma_f32 v123, v123, v115, v115
	v_fma_f32 v124, v124, v116, v116
	v_fma_f32 v125, v125, v117, v117
	v_fma_f32 v126, v126, v118, v118
	v_fma_f32 v127, v127, v119, v119
	v_fma_f32 v128, v128, v120, v120
	v_mul_f32_e32 v121, 0x3f4c422a, v121
	v_mul_f32_e32 v122, 0x3f4c422a, v122
	v_mul_f32_e32 v123, 0x3f4c422a, v123
	v_mul_f32_e32 v124, 0x3f4c422a, v124
	v_mul_f32_e32 v125, 0x3f4c422a, v125
	v_mul_f32_e32 v126, 0x3f4c422a, v126
	v_mul_f32_e32 v127, 0x3f4c422a, v127
	v_mul_f32_e32 v128, 0x3f4c422a, v128
	v_add_f32_e32 v121, v121, v121
	v_add_f32_e32 v122, v122, v122
	v_add_f32_e32 v123, v123, v123
	v_add_f32_e32 v124, v124, v124
	v_add_f32_e32 v125, v125, v125
	v_add_f32_e32 v126, v126, v126
	v_add_f32_e32 v127, v127, v127
	v_add_f32_e32 v128, v128, v128
	v_mul_f32_e32 v121, 0x3fb8aa3b, v121
	v_mul_f32_e32 v122, 0x3fb8aa3b, v122
	v_mul_f32_e32 v123, 0x3fb8aa3b, v123
	v_mul_f32_e32 v124, 0x3fb8aa3b, v124
	v_mul_f32_e32 v125, 0x3fb8aa3b, v125
	v_mul_f32_e32 v126, 0x3fb8aa3b, v126
	v_mul_f32_e32 v127, 0x3fb8aa3b, v127
	v_mul_f32_e32 v128, 0x3fb8aa3b, v128
	v_exp_f32_e32 v121, v121
	v_exp_f32_e32 v122, v122
	v_exp_f32_e32 v123, v123
	v_exp_f32_e32 v124, v124
	v_exp_f32_e32 v125, v125
	v_exp_f32_e32 v126, v126
	v_exp_f32_e32 v127, v127
	v_exp_f32_e32 v128, v128
	v_mul_f32_e32 v129, 0.5, v113
	v_mul_f32_e32 v130, 0.5, v114
	v_mul_f32_e32 v131, 0.5, v115
	v_mul_f32_e32 v132, 0.5, v116
	v_mul_f32_e32 v133, 0.5, v117
	v_mul_f32_e32 v134, 0.5, v118
	v_mul_f32_e32 v135, 0.5, v119
	v_mul_f32_e32 v138, 0.5, v120
	v_add_f32_e32 v121, 1.0, v121
	v_add_f32_e32 v122, 1.0, v122
	v_add_f32_e32 v123, 1.0, v123
	v_add_f32_e32 v124, 1.0, v124
	v_add_f32_e32 v125, 1.0, v125
	v_add_f32_e32 v126, 1.0, v126
	v_add_f32_e32 v127, 1.0, v127
	v_add_f32_e32 v128, 1.0, v128
	v_rcp_f32_e32 v121, v121
	v_rcp_f32_e32 v122, v122
	v_rcp_f32_e32 v123, v123
	v_rcp_f32_e32 v124, v124
	v_rcp_f32_e32 v125, v125
	v_rcp_f32_e32 v126, v126
	v_rcp_f32_e32 v127, v127
	v_rcp_f32_e32 v128, v128
	v_fma_f32 v121, v121, -2.0, 1.0
	v_fma_f32 v122, v122, -2.0, 1.0
	v_fma_f32 v123, v123, -2.0, 1.0
	v_fma_f32 v124, v124, -2.0, 1.0
	v_fma_f32 v125, v125, -2.0, 1.0
	v_fma_f32 v126, v126, -2.0, 1.0
	v_fma_f32 v127, v127, -2.0, 1.0
	v_fma_f32 v128, v128, -2.0, 1.0
	v_add_f32_e32 v121, 1.0, v121
	v_add_f32_e32 v122, 1.0, v122
	v_add_f32_e32 v123, 1.0, v123
	v_add_f32_e32 v124, 1.0, v124
	v_add_f32_e32 v125, 1.0, v125
	v_add_f32_e32 v126, 1.0, v126
	v_add_f32_e32 v127, 1.0, v127
	v_add_f32_e32 v128, 1.0, v128
	v_fma_f32 v113, v129, v121, -v178
	v_fma_f32 v114, v130, v122, -v180
	v_fma_f32 v115, v131, v123, -v182
	v_fma_f32 v116, v132, v124, -v184
	v_fma_f32 v117, v133, v125, -v186
	v_fma_f32 v118, v134, v126, -v188
	v_fma_f32 v119, v135, v127, -v16
	v_fma_f32 v120, v138, v128, -v18
	v_mul_f32_e32 v113, v179, v113
	v_mul_f32_e32 v114, v181, v114
	v_mul_f32_e32 v115, v183, v115
	v_mul_f32_e32 v116, v185, v116
	v_mul_f32_e32 v117, v187, v117
	v_mul_f32_e32 v118, v189, v118
	v_mul_f32_e32 v119, v17, v119
	v_mul_f32_e32 v120, v19, v120
	v_fma_f32 v113, v232, v113, v233
	v_fma_f32 v114, v232, v114, v233
	v_fma_f32 v115, v232, v115, v233
	v_fma_f32 v116, v232, v116, v233
	v_fma_f32 v117, v232, v117, v233
	v_fma_f32 v118, v232, v118, v233
	v_fma_f32 v119, v232, v119, v233
	v_fma_f32 v120, v232, v120, v233
	v_cvt_pk_bf16_f32 v236, v113, v114
	v_cvt_pk_bf16_f32 v237, v115, v116
	v_cvt_pk_bf16_f32 v238, v117, v118
	v_cvt_pk_bf16_f32 v239, v119, v120
	ds_write_b128 v9, v[236:239] offset:17424
	s_add_u32 s20, s20, 0x100
	s_addc_u32 s21, s21, 0
	v_lshl_add_u64 v[2:3], v[2:3], 0, s[36:37]
	v_lshl_add_u64 v[4:5], v[4:5], 0, s[36:37]
	v_add_u32_e32 v9, 0x8800, v9
	s_cmpk_eq_i32 s20, 0x200
	s_cbranch_scc0 .LBB0_162
	s_lshl_b32 s13, s13, 1
	s_add_i32 s20, s13, s28
	s_ashr_i32 s21, s20, 31
	s_lshl_b64 s[22:23], s[20:21], 16
	v_lshl_add_u64 v[0:1], v[82:83], 0, s[22:23]
	s_waitcnt lgkmcnt(0)
	s_barrier
	global_load_dwordx4 v[72:75], v[0:1], off offset:16
	global_load_dwordx4 v[76:79], v[0:1], off
	v_mov_b32_e32 v0, 0
	v_lshl_add_u64 v[98:99], v[90:91], 0, s[22:23]
	s_mov_b32 s13, 0
	v_mov_b32_e32 v93, v107
	s_mov_b32 s21, 0
	v_mov_b32_e32 v1, v0
	v_mov_b32_e32 v2, v0
	v_mov_b32_e32 v3, v0
	v_mov_b32_e32 v4, v0
	v_mov_b32_e32 v5, v0
	v_mov_b32_e32 v6, v0
	v_mov_b32_e32 v7, v0
	v_mov_b32_e32 v8, v0
	v_mov_b32_e32 v9, v0
	v_mov_b32_e32 v10, v0
	v_mov_b32_e32 v11, v0
	v_mov_b32_e32 v12, v0
	v_mov_b32_e32 v13, v0
	v_mov_b32_e32 v14, v0
	v_mov_b32_e32 v15, v0
	v_mov_b32_e32 v16, v0
	v_mov_b32_e32 v17, v0
	v_mov_b32_e32 v18, v0
	v_mov_b32_e32 v19, v0
	v_mov_b32_e32 v20, v0
	v_mov_b32_e32 v21, v0
	v_mov_b32_e32 v22, v0
	v_mov_b32_e32 v23, v0
	v_mov_b32_e32 v24, v0
	v_mov_b32_e32 v25, v0
	v_mov_b32_e32 v26, v0
	v_mov_b32_e32 v27, v0
	v_mov_b32_e32 v28, v0
	v_mov_b32_e32 v29, v0
	v_mov_b32_e32 v30, v0
	v_mov_b32_e32 v31, v0
	v_mov_b32_e32 v32, v0
	v_mov_b32_e32 v33, v0
	v_mov_b32_e32 v34, v0
	v_mov_b32_e32 v35, v0
	v_mov_b32_e32 v36, v0
	v_mov_b32_e32 v37, v0
	v_mov_b32_e32 v38, v0
	v_mov_b32_e32 v39, v0
	v_mov_b32_e32 v40, v0
	v_mov_b32_e32 v41, v0
	v_mov_b32_e32 v42, v0
	v_mov_b32_e32 v43, v0
	v_mov_b32_e32 v44, v0
	v_mov_b32_e32 v45, v0
	v_mov_b32_e32 v46, v0
	v_mov_b32_e32 v47, v0
	v_mov_b32_e32 v48, v0
	v_mov_b32_e32 v49, v0
	v_mov_b32_e32 v50, v0
	v_mov_b32_e32 v51, v0
	v_mov_b32_e32 v52, v0
	v_mov_b32_e32 v53, v0
	v_mov_b32_e32 v54, v0
	v_mov_b32_e32 v55, v0
	v_mov_b32_e32 v56, v0
	v_mov_b32_e32 v57, v0
	v_mov_b32_e32 v58, v0
	v_mov_b32_e32 v59, v0
	v_mov_b32_e32 v60, v0
	v_mov_b32_e32 v61, v0
	v_mov_b32_e32 v62, v0
	v_mov_b32_e32 v63, v0
	s_waitcnt vmcnt(1)
	v_mov_b64_e32 v[68:69], v[72:73]
	s_waitcnt vmcnt(0)
	v_mov_b64_e32 v[64:65], v[76:77]
	v_mov_b64_e32 v[66:67], v[78:79]
	v_mov_b64_e32 v[70:71], v[74:75]
	s_branch .LBB0_165
